# v6: v5 + GDN chain halves paired on one XCD via per-XCD chain ticket counters (second reader of the chunk records hits L2)
# baseline (speedup 1.0000x reference)
; __device__ __forceinline__ float wave_max(float v) { v = fmaxf(v, xshfl<1>(v)); v = fmaxf(v, xshfl<2>(v)); v = fmaxf(v, xshfl<4>(v)); v = fmaxf(v, xshfl<8>(v)); v = fmaxf(v, xshfl<16>(v)); return half_max(v); }
; #define LAUNDER_TID() int tid = tid0; asm volatile("" : "+v"(tid)); const int lane = tid & 63, wave = __builtin_amdgcn_readfirstlane(tid >> 6), gw = bx * NWAVES + wave; (void)lane; (void)gw
; #define TBR(i) __builtin_amdgcn_readfirstlane((int)TB[i])
; #define swa_q_gain INP(8)
; #define swa_k_gain INP(9)
; __global__ void __launch_bounds__(NTHREADS, 2) fwd_kernel(Args args) {
;     ...
;             const int nchain = nseq * 32, nqb = Tp / 256, nblk = nseq * 8 * nqb;
;             float bd, bs;
;             const float* dqg = diff_q_gain + l * 64; const float* sqg = swa_q_gain + l * 128;
;             { int ln_ = tid0; asm volatile("" : "+v"(ln_)); const int ln = ln_ & 63; const float* dkg = diff_k_gain + l * 64; const float* skg = swa_k_gain + l * 128;
;               float gq = fabsf(dqg[ln]), gk = fabsf(dkg[ln]);
;               float sq_ = fmaxf(fabsf(sqg[ln]), fabsf(sqg[64 + ln])), sk_ = fmaxf(fabsf(skg[ln]), fabsf(skg[64 + ln]));
;               gq = wave_max(gq); gk = wave_max(gk); sq_ = wave_max(sq_); sk_ = wave_max(sk_);
;               bd = 8.0f * gq * gk * 1.02f; bs = 11.3137085f * sq_ * sk_ * 1.02f; }
;             const bool fixd = (bd * LOG2E < 60.f) && (bd == bd), fixs = (bs * LOG2E < 60.f) && (bs == bs);
;     ...
;             AttnParams PD{dqg, nullptr, diff_lambda + l * 256, diff_norm_gain + l * 128, UNIFORM_F(bd)};
;             AttnParams PS{sqg, swa_sink + l * 8, nullptr, nullptr, UNIFORM_F(bs)};
;             DIFF_TABLE(bd, fixd);
;             const int ndiff = TBR(T_NDF);
;             const int item_lo = (rep == 1 && (DUP_PHASE == 8 || DUP_PHASE == 11)) ? nchain : ((rep == 1 && DUP_PHASE == 9) ? nchain + ndiff : 0);
;             const int total = (rep == 1 && DUP_PHASE == 5) ? nchain : ((rep == 1 && (DUP_PHASE == 8 || DUP_PHASE == 11)) ? nchain + ndiff : nchain + ndiff + nblk);
; #pragma unroll 1
;             for (;;) {
;                 LAUNDER_TID();
;                 if (tid == 0) MISC[0] = __hip_atomic_fetch_add(ctl + CW_QUEUE + it * 64 + rep * 32, 1u, __ATOMIC_RELAXED, __HIP_MEMORY_SCOPE_AGENT);
;                 __syncthreads();
;                 const int item = __builtin_amdgcn_readfirstlane((int)MISC[0]) + item_lo;
.LBB0_822:
	s_or_b64 exec, exec, s[18:19]
	s_xor_b64 s[6:7], s[6:7], -1
	v_writelane_b32 v255, s6, 10
	s_add_i32 s22, s22, 3
	s_lshl_b32 s18, s31, 6
	v_writelane_b32 v255, s7, 11
	v_readlane_b32 s6, v254, 26
	s_mov_b32 s19, s61
	s_lshl_b32 s16, s85, s22
	s_lshl_b32 s60, s6, 8
	s_lshl_b32 s6, s6, 3
	s_lshl_b64 s[18:19], s[18:19], 2
	v_readlane_b32 s3, v252, 32
	s_add_u32 s18, s3, s18
	v_readlane_b32 s3, v252, 33
	s_addc_u32 s19, s3, s19
	v_readlane_b32 s7, v254, 27
	v_writelane_b32 v254, s18, 32
	s_lshr_b32 s17, s35, 5
	v_cmp_u_f32_e32 vcc, v2, v2
	v_writelane_b32 v254, s19, 33
	s_mov_b32 s7, s61
	v_readlane_b32 s22, v254, 16
	v_readlane_b32 s23, v254, 17
	s_and_b64 s[18:19], s[22:23], exec
	s_cselect_b32 s3, 8, 6
	s_cselect_b32 s29, 14, 12
	v_writelane_b32 v255, s3, 20
	s_add_i32 s3, s72, -1
	v_writelane_b32 v255, s3, 22
	s_add_i32 s3, s72, -3
	s_xor_b64 s[4:5], s[4:5], -1
	v_writelane_b32 v255, s3, 26
	s_or_b64 s[4:5], vcc, s[4:5]
	v_writelane_b32 v255, s4, 30
	s_add_i32 s19, s72, -2
	s_waitcnt lgkmcnt(0)
	v_writelane_b32 v255, s5, 31
	s_lshl_b64 s[4:5], s[60:61], 2
	s_add_u32 s4, s10, s4
	s_addc_u32 s5, s11, s5
	v_writelane_b32 v254, s4, 40
	s_add_u32 s38, s12, s8
	s_addc_u32 s39, s13, s9
	v_writelane_b32 v254, s5, 41
	s_lshl_b64 s[4:5], s[6:7], 2
	s_add_u32 s4, s14, s4
	s_addc_u32 s5, s15, s5
	v_writelane_b32 v254, s4, 42
	s_barrier
	s_nop 0
	v_writelane_b32 v254, s5, 43
	s_and_b64 s[4:5], s[22:23], exec
	v_readlane_b32 s3, v254, 1
	s_cselect_b32 s84, 32, 0x80
	v_writelane_b32 v255, s17, 14
	v_mov_b32_e32 v2, s3
	ds_read_b32 v2, v2
	s_waitcnt lgkmcnt(0)
	v_readfirstlane_b32 s4, v2
	v_cvt_f32_u32_e32 v2, s17
	s_add_i32 s3, s4, s84
	s_sub_i32 s4, 0, s17
	v_writelane_b32 v254, s3, 30
	v_rcp_iflag_f32_e32 v2, v2
	s_add_i32 s23, s3, s16
	v_mul_f32_e32 v2, 0x4f7ffffe, v2
	v_cvt_u32_f32_e32 v2, v2
	s_nop 0
	v_readfirstlane_b32 s5, v2
	s_mul_i32 s4, s4, s5
	s_mul_hi_u32 s4, s5, s4
	s_add_i32 s3, s5, s4
	v_writelane_b32 v255, s3, 38
	s_ashr_i32 s3, s85, 31
	v_writelane_b32 v255, s3, 40
	s_abs_i32 s3, s85
	v_cvt_f32_u32_e32 v2, s3
	s_sub_i32 s4, 0, s3
	v_writelane_b32 v255, s3, 42
	v_rcp_iflag_f32_e32 v2, v2
	s_nop 0
	v_mul_f32_e32 v2, 0x4f7ffffe, v2
	v_cvt_u32_f32_e32 v2, v2
	s_nop 0
	v_readfirstlane_b32 s5, v2
	s_mul_i32 s4, s4, s5
	s_mul_hi_u32 s4, s5, s4
	s_add_i32 s3, s5, s4
	v_writelane_b32 v255, s3, 46
	v_readlane_b32 s3, v254, 34
	s_sub_i32 s4, 0, s3
	s_nop 0
	v_cvt_f32_u32_e32 v2, s3
	v_rcp_iflag_f32_e32 v2, v2
	s_nop 0
	v_mul_f32_e32 v2, 0x4f7ffffe, v2
	v_cvt_u32_f32_e32 v2, v2
	s_nop 0
	v_readfirstlane_b32 s5, v2
	v_cvt_f32_u32_e32 v2, s85
	s_mul_i32 s4, s4, s5
	s_mul_hi_u32 s4, s5, s4
	s_add_i32 s3, s5, s4
	v_rcp_iflag_f32_e32 v2, v2
	s_sub_i32 s4, 0, s85
	v_writelane_b32 v255, s3, 50
	v_mul_f32_e32 v2, 0x4f7ffffe, v2
	v_cvt_u32_f32_e32 v2, v2
	s_nop 0
	v_readfirstlane_b32 s5, v2
	s_mul_i32 s4, s4, s5
	s_mul_hi_u32 s4, s5, s4
	s_add_i32 s3, s5, s4
	v_writelane_b32 v255, s3, 52
	s_add_i32 s3, s35, -1
	v_writelane_b32 v255, s85, 0
	v_writelane_b32 v254, s3, 36
	s_add_i32 s3, s72, -5
	v_writelane_b32 v255, s29, 18
	v_writelane_b32 v254, s3, 38
	v_writelane_b32 v255, s84, 34
	s_mov_b32 s32, 0
	s_branch .LBB0_825

; #define LAUNDER_TID() int tid = tid0; asm volatile("" : "+v"(tid)); const int lane = tid & 63, wave = __builtin_amdgcn_readfirstlane(tid >> 6), gw = bx * NWAVES + wave; (void)lane; (void)gw
; __global__ void __launch_bounds__(NTHREADS, 2) fwd_kernel(Args args) {
;     ...
;             for (;;) {
;                 LAUNDER_TID();
;                 if (tid == 0) MISC[0] = __hip_atomic_fetch_add(ctl + CW_QUEUE + it * 64 + rep * 32, 1u, __ATOMIC_RELAXED, __HIP_MEMORY_SCOPE_AGENT);
;                 __syncthreads();
.LBB0_825:
	v_mov_b32_e32 v192, v0
	s_nop 0
	v_readfirstlane_b32 s10, v192
	v_cmp_eq_u32_e32 vcc, 0, v192
	s_and_saveexec_b64 s[4:5], vcc
	s_cbranch_execz .LBB0_829
	s_mov_b64 s[8:9], exec
	v_mbcnt_lo_u32_b32 v2, s8, 0
	v_mbcnt_hi_u32_b32 v2, s9, v2
	v_cmp_eq_u32_e32 vcc, 0, v2
	s_and_saveexec_b64 s[6:7], vcc
	s_cbranch_execz .LBB0_828
	s_bcnt1_i32_b64 s8, s[8:9]
	v_mov_b32_e32 v3, s8
	v_readlane_b32 s8, v254, 32
	v_readlane_b32 s9, v254, 33
	s_nop 4
	s_and_b32 s100, s2, 7
	s_lshl_b32 s100, s100, 2
	s_add_i32 s100, s100, 4
	s_cmp_eq_u32 s32, 0
	s_cselect_b32 s100, s100, 0
	v_mov_b32_e32 v5, s100
	global_atomic_add v3, v5, v3, s[8:9] sc0

; __device__ __forceinline__ float bflo(unsigned w) { return __uint_as_float(w << 16); }
; #define TBR(i) __builtin_amdgcn_readfirstlane((int)TB[i])
; template <int MODE, bool FIXED>
; __device__ __forceinline__ void attn_unit(LAS unsigned char* lds, unsigned char* ws, const AttnParams& P, int l, int Tp, int sq, int h, int qb, int part, int np, int pslot, int tid, int wave, int lane) {
;     ...
;             const bf16* qp = PROJ + (size_t)(seq0 + q0 + wave * 32 + r32) * LDP + qcol + mp * 64 + hi * 8;
;             float qf[NDD][8]; float ss = 0.f;
; #pragma unroll
;             for (int d0 = 0; d0 < NDD; ++d0) { const v4u w = *(const v4u*)(qp + d0 * 16);
;                 qf[d0][0] = bflo(w.x); qf[d0][1] = bfhi(w.x); qf[d0][2] = bflo(w.y); qf[d0][3] = bfhi(w.y); qf[d0][4] = bflo(w.z); qf[d0][5] = bfhi(w.z); qf[d0][6] = bflo(w.w); qf[d0][7] = bfhi(w.w);
; #pragma unroll
;                 for (int e = 0; e < 8; ++e) ss += qf[d0][e] * qf[d0][e]; }
; __global__ void __launch_bounds__(NTHREADS, 2) fwd_kernel(Args args) {
;     ...
;                 const int item = __builtin_amdgcn_readfirstlane((int)MISC[0]) + item_lo;
;                 __syncthreads();
;                 if (item >= total) break;
;                 if (PH4_ON(0) && item < nchain) { gdn_scan_unit(lds, ws, Tp, item >> 5, (item >> 2) & 7, (item >> 1) & 1, item & 1, tid, wave, lane); }
;                 else if (PH4_ON(1) && item < nchain + ndiff) { const int u = item - nchain, per = nseq * nqb;
;                     const int g = u / per, un = u - g * per, e = TBR(T_GT + g), hh = e & 0xff, part = (e >> 8) & 0xff, np = e >> 16, sq = un / nqb, qb = un - sq * nqb;
;                     const int pslot = (np > 1) ? TBR(T_PB + hh) + un * np + part : -1;
;                     const bool pe_ = (DUP_PHASE == 11 && rep == 1);
;                     if (fixd) attn_unit<1, true>(lds, ws, PD, l, Tp, sq, hh, qb, pe_ ? 999999 : part, pe_ ? 1000000 : np, pe_ ? PART_SLOTS - 1 : pslot, tid, wave, lane); else if (DUP_PHASE < 0) attn_unit<1, false>(lds, ws, PD, l, Tp, sq, hh, qb, 0, 1, -1, tid, wave, lane); }
;                 else if (PH4_ON(2)) { const int u = item - nchain - ndiff;
;                     if (fixs) attn_unit<0, true>(lds, ws, PS, l, Tp, u / (8 * nqb), (u / nqb) & 7, u % nqb, 0, 1, -1, tid, wave, lane); else attn_unit<0, false>(lds, ws, PS, l, Tp, u / (8 * nqb), (u / nqb) & 7, u % nqb, 0, 1, -1, tid, wave, lane); }
.LBB0_829:
	s_or_b64 exec, exec, s[4:5]
	v_readlane_b32 s3, v254, 2
	s_waitcnt lgkmcnt(0)
	s_barrier
	v_mov_b32_e32 v2, s3
	ds_read_b32 v2, v2
	s_mov_b64 s[4:5], -1
	s_waitcnt lgkmcnt(0)
	s_barrier
	v_readfirstlane_b32 s30, v2
	s_cmp_lg_u32 s32, 0
	s_cbranch_scc1 .Lq_global
	s_lshr_b32 s101, s84, 3
	s_cmp_lt_u32 s30, s101
	s_cbranch_scc1 .Lq_chain
	s_mov_b32 s32, 1
	s_branch .LBB0_825
.Lq_chain:
	s_and_b32 s100, s2, 7
	s_lshr_b32 s101, s30, 1
	s_lshl_b32 s101, s101, 3
	s_add_i32 s101, s101, s100
	s_lshl_b32 s101, s101, 1
	s_and_b32 s30, s30, 1
	s_or_b32 s30, s30, s101
	s_branch .Lq_have
.Lq_global:
	s_add_i32 s30, s30, s84
.Lq_have:
	s_cmp_ge_i32 s30, s23
	s_cbranch_scc1 .LBB0_824
	s_ashr_i32 s31, s10, 6
	v_and_b32_e32 v193, 63, v192
	s_cmp_ge_i32 s30, s84
	s_cbranch_scc0 .LBB0_971
	v_readlane_b32 s3, v254, 30
	v_lshrrev_b32_e32 v194, 5, v193
	s_cmp_ge_i32 s30, s3
	v_and_b32_e32 v195, 31, v192
	v_lshlrev_b32_e32 v170, 4, v194
	s_cbranch_scc0 .LBB0_883
	v_readlane_b32 s3, v254, 30
	s_sub_i32 s4, s30, s3
	s_abs_i32 s6, s4
	v_readlane_b32 s3, v255, 38
	s_mul_hi_u32 s7, s6, s3
	v_readlane_b32 s3, v255, 14
	s_mul_i32 s8, s7, s3
	s_sub_i32 s8, s6, s8
	s_ashr_i32 s5, s4, 31
	s_add_i32 s9, s7, 1
	s_sub_i32 s10, s8, s3
	s_cmp_ge_u32 s8, s3
	s_cselect_b32 s7, s9, s7
	s_cselect_b32 s8, s10, s8
	s_add_i32 s9, s7, 1
	s_cmp_ge_u32 s8, s3
	s_cselect_b32 s7, s9, s7
	s_xor_b32 s7, s7, s5
	v_readlane_b32 s3, v255, 40
	s_sub_i32 s7, s7, s5
	s_xor_b32 s5, s5, s3
	v_readlane_b32 s3, v255, 46
	s_mul_hi_u32 s8, s6, s3
	v_readlane_b32 s3, v255, 42
	s_mul_i32 s9, s8, s3
	s_sub_i32 s6, s6, s9
	s_add_i32 s9, s8, 1
	s_sub_i32 s10, s6, s3
	s_cmp_ge_u32 s6, s3
	s_cselect_b32 s8, s9, s8
	s_cselect_b32 s6, s10, s6
	s_add_i32 s9, s8, 1
	s_cmp_ge_u32 s6, s3
	s_cselect_b32 s6, s9, s8
	s_xor_b32 s6, s6, s5
	s_sub_i32 s5, s6, s5
	s_mul_i32 s6, s5, s85
	s_and_b32 s18, s5, 7
	s_sub_i32 s4, s4, s6
	s_lshl_b32 s27, s4, 8
	s_lshl_b32 s4, s5, 5
	s_add_i32 s5, s18, 1
	v_cvt_f32_ubyte0_e32 v2, s5
	s_mov_b32 s3, 0x42fc0000
	v_cmp_lt_f32_e32 vcc, s3, v2
	s_lshl_b32 s12, s7, s29
	s_lshl_b32 s26, s18, 7
	v_cndmask_b32_e32 v3, 0, v250, vcc
	v_sub_f32_e32 v2, v3, v2
	v_exp_f32_e32 v2, v2
	s_and_b32 s15, s4, 0x80
	s_and_b64 s[4:5], vcc, exec
	s_cselect_b32 s4, 0xffffffc0, 0
	s_waitcnt vmcnt(0)
	v_ldexp_f32 v72, v2, s4
	s_add_i32 s4, s27, 0xffffff80
	s_ashr_i32 s4, s4, 6
	s_max_i32 s14, s4, 0
	s_add_i32 s4, s27, 0x180
	s_ashr_i32 s22, s4, 6
	s_lshl_b32 s13, s31, 8
	v_lshlrev_b32_e32 v135, 2, v194
	v_or_b32_e32 v2, s12, v195
	v_lshlrev_b32_e32 v5, 3, v194
	s_mov_b64 s[4:5], exec
	v_readlane_b32 s6, v255, 30
	v_readlane_b32 s7, v255, 31
	s_and_b64 s[6:7], s[4:5], s[6:7]
	s_xor_b64 s[8:9], s[6:7], s[4:5]
	s_mov_b64 exec, s[6:7]
	s_cbranch_execz .LBB0_861
	s_lshl_b32 s4, s31, 5
	s_add_i32 s44, s27, s4
	v_add_u32_e32 v6, s44, v2
	v_mov_b64_e32 v[2:3], s[50:51]
	v_mad_i64_i32 v[2:3], s[4:5], v6, s70, v[2:3]
	s_lshl_b32 s60, s26, 1
	v_lshl_add_u64 v[2:3], v[2:3], 0, s[60:61]
	v_mov_b32_e32 v171, v4
	v_lshl_add_u64 v[2:3], v[2:3], 0, v[170:171]
	s_mov_b64 s[4:5], 0x2000
	s_movk_i32 s3, 0x2000
	v_lshl_add_u64 v[14:15], v[2:3], 0, s[4:5]
	v_add_co_u32_e32 v2, vcc, s3, v2
	global_load_dwordx4 v[24:27], v[14:15], off offset:32
	global_load_dwordx4 v[28:31], v[14:15], off offset:64
	global_load_dwordx4 v[34:37], v[14:15], off offset:96
	global_load_dwordx4 v[56:59], v[14:15], off offset:128
	v_addc_co_u32_e32 v3, vcc, 0, v3, vcc
	global_load_dwordx4 v[6:9], v[14:15], off offset:160
	global_load_dwordx4 v[60:63], v[2:3], off
	global_load_dwordx4 v[10:13], v[14:15], off offset:192
	s_nop 0
	global_load_dwordx4 v[14:17], v[14:15], off offset:224
	s_add_i32 s6, s13, 0
	s_add_i32 s6, s6, 0x21000
	s_min_i32 s45, s22, s72
	v_cmp_gt_u32_e64 s[4:5], 32, v193
	v_lshl_add_u32 v171, v195, 2, s6
	s_cmp_ge_i32 s14, s45
	v_lshl_add_u32 v174, v135, 2, s6
	s_waitcnt vmcnt(7)
	v_lshlrev_b32_e32 v22, 16, v24
	v_and_b32_e32 v23, 0xffff0000, v24
	s_waitcnt vmcnt(5)
	v_lshlrev_b32_e32 v42, 16, v36
	v_and_b32_e32 v43, 0xffff0000, v36
	v_lshlrev_b32_e32 v40, 16, v37
	v_and_b32_e32 v41, 0xffff0000, v37
	v_lshlrev_b32_e32 v46, 16, v34
	s_waitcnt vmcnt(2)
	v_and_b32_e32 v39, 0xffff0000, v60
	v_lshlrev_b32_e32 v38, 16, v60
	v_mul_f32_e32 v90, v39, v39
	v_lshlrev_b32_e32 v36, 16, v61
	v_and_b32_e32 v37, 0xffff0000, v61
	v_pk_fma_f32 v[90:91], v[38:39], v[38:39], v[90:91] op_sel_hi:[1,1,0]
	v_mul_f32_e32 v92, v37, v37
	v_pk_fma_f32 v[90:91], v[36:37], v[36:37], v[90:91]
	v_and_b32_e32 v47, 0xffff0000, v34
	v_lshlrev_b32_e32 v44, 16, v35
	v_and_b32_e32 v45, 0xffff0000, v35
	v_lshlrev_b32_e32 v34, 16, v62
	v_and_b32_e32 v35, 0xffff0000, v62
	v_pk_add_f32 v[90:91], v[92:93], v[90:91] op_sel_hi:[0,1]
	v_mul_f32_e32 v94, v35, v35
	v_pk_fma_f32 v[90:91], v[34:35], v[34:35], v[90:91]
	v_lshlrev_b32_e32 v20, 16, v25
	v_and_b32_e32 v21, 0xffff0000, v25
	v_lshlrev_b32_e32 v18, 16, v26
	v_and_b32_e32 v19, 0xffff0000, v26
	v_lshlrev_b32_e32 v2, 16, v27
	v_and_b32_e32 v3, 0xffff0000, v27
	v_lshlrev_b32_e32 v26, 16, v30
	v_and_b32_e32 v27, 0xffff0000, v30
	v_lshlrev_b32_e32 v24, 16, v31
	v_and_b32_e32 v25, 0xffff0000, v31
	v_lshlrev_b32_e32 v30, 16, v63
	v_and_b32_e32 v31, 0xffff0000, v63
	v_pk_add_f32 v[90:91], v[94:95], v[90:91] op_sel_hi:[0,1]
	v_mul_f32_e32 v96, v31, v31
	v_pk_fma_f32 v[90:91], v[30:31], v[30:31], v[90:91]
	v_lshlrev_b32_e32 v54, 16, v56
	v_pk_add_f32 v[90:91], v[96:97], v[90:91] op_sel_hi:[0,1]
	v_and_b32_e32 v55, 0xffff0000, v56
	v_lshlrev_b32_e32 v52, 16, v57
	v_and_b32_e32 v53, 0xffff0000, v57
	v_lshlrev_b32_e32 v56, 16, v6
	v_and_b32_e32 v57, 0xffff0000, v6
	v_mul_f32_e32 v6, v23, v23
	v_pk_fma_f32 v[90:91], v[22:23], v[22:23], v[90:91]
; __device__ __forceinline__ float bflo(unsigned w) { return __uint_as_float(w << 16); }
; __device__ __forceinline__ float bfhi(unsigned w) { return __uint_as_float(w & 0xffff0000u); }
; __device__ __forceinline__ float bflo(unsigned w) { return __uint_as_float(w << 16); }
; __device__ __forceinline__ float bfhi(unsigned w) { return __uint_as_float(w & 0xffff0000u); }
; template <int MODE, bool FIXED>
; __device__ __forceinline__ void attn_unit(LAS unsigned char* lds, unsigned char* ws, const AttnParams& P, int l, int Tp, int sq, int h, int qb, int part, int np, int pslot, int tid, int wave, int lane) {
;     ...
;             float qf[NDD][8]; float ss = 0.f;
; #pragma unroll
;             for (int d0 = 0; d0 < NDD; ++d0) { const v4u w = *(const v4u*)(qp + d0 * 16);
;                 qf[d0][0] = bflo(w.x); qf[d0][1] = bfhi(w.x); qf[d0][2] = bflo(w.y); qf[d0][3] = bfhi(w.y); qf[d0][4] = bflo(w.z); qf[d0][5] = bfhi(w.z); qf[d0][6] = bflo(w.w); qf[d0][7] = bfhi(w.w);
; #pragma unroll
;                 for (int e = 0; e < 8; ++e) ss += qf[d0][e] * qf[d0][e]; }
;             ss = half_sum(ss);
	v_lshlrev_b32_e32 v50, 16, v58
	v_pk_add_f32 v[90:91], v[6:7], v[90:91] op_sel_hi:[0,1]
	v_and_b32_e32 v51, 0xffff0000, v58
	v_mul_f32_e32 v58, v21, v21
	v_pk_fma_f32 v[90:91], v[20:21], v[20:21], v[90:91]
	v_lshlrev_b32_e32 v48, 16, v59
	v_and_b32_e32 v49, 0xffff0000, v59
	v_pk_add_f32 v[58:59], v[58:59], v[90:91] op_sel_hi:[0,1]
	v_mul_f32_e32 v60, v19, v19
	v_pk_fma_f32 v[58:59], v[18:19], v[18:19], v[58:59]
	v_mul_f32_e32 v62, v3, v3
	v_pk_add_f32 v[58:59], v[60:61], v[58:59] op_sel_hi:[0,1]
	v_pk_fma_f32 v[58:59], v[2:3], v[2:3], v[58:59]
	v_lshlrev_b32_e32 v32, 16, v28
	v_and_b32_e32 v33, 0xffff0000, v28
	v_pk_add_f32 v[58:59], v[62:63], v[58:59] op_sel_hi:[0,1]
	v_mul_f32_e32 v64, v33, v33
	v_pk_fma_f32 v[58:59], v[32:33], v[32:33], v[58:59]
	v_lshlrev_b32_e32 v28, 16, v29
	v_and_b32_e32 v29, 0xffff0000, v29
	v_pk_add_f32 v[58:59], v[64:65], v[58:59] op_sel_hi:[0,1]
	v_mul_f32_e32 v66, v29, v29
	v_pk_fma_f32 v[58:59], v[28:29], v[28:29], v[58:59]
	v_mul_f32_e32 v68, v27, v27
	v_pk_add_f32 v[58:59], v[66:67], v[58:59] op_sel_hi:[0,1]
	v_pk_fma_f32 v[58:59], v[26:27], v[26:27], v[58:59]
	v_mul_f32_e32 v70, v25, v25
	v_pk_add_f32 v[58:59], v[68:69], v[58:59] op_sel_hi:[0,1]
	v_pk_fma_f32 v[58:59], v[24:25], v[24:25], v[58:59]
	v_mul_f32_e32 v74, v47, v47
	v_pk_add_f32 v[58:59], v[70:71], v[58:59] op_sel_hi:[0,1]
	v_pk_fma_f32 v[58:59], v[46:47], v[46:47], v[58:59]
	v_mul_f32_e32 v76, v45, v45
	v_pk_add_f32 v[58:59], v[74:75], v[58:59] op_sel_hi:[0,1]
	v_pk_fma_f32 v[58:59], v[44:45], v[44:45], v[58:59]
	v_mul_f32_e32 v78, v43, v43
	v_pk_add_f32 v[58:59], v[76:77], v[58:59] op_sel_hi:[0,1]
	v_pk_fma_f32 v[58:59], v[42:43], v[42:43], v[58:59]
	v_mul_f32_e32 v80, v41, v41
	v_pk_add_f32 v[58:59], v[78:79], v[58:59] op_sel_hi:[0,1]
	v_pk_fma_f32 v[58:59], v[40:41], v[40:41], v[58:59]
	v_mul_f32_e32 v82, v55, v55
	v_pk_add_f32 v[58:59], v[80:81], v[58:59] op_sel_hi:[0,1]
	v_pk_fma_f32 v[58:59], v[54:55], v[54:55], v[58:59]
	v_mul_f32_e32 v84, v53, v53
	v_pk_add_f32 v[58:59], v[82:83], v[58:59] op_sel_hi:[0,1]
	v_pk_fma_f32 v[58:59], v[52:53], v[52:53], v[58:59]
	v_mul_f32_e32 v86, v51, v51
	v_pk_add_f32 v[58:59], v[84:85], v[58:59] op_sel_hi:[0,1]
	v_pk_fma_f32 v[58:59], v[50:51], v[50:51], v[58:59]
	v_mul_f32_e32 v88, v49, v49
	v_pk_add_f32 v[58:59], v[86:87], v[58:59] op_sel_hi:[0,1]
	v_pk_fma_f32 v[58:59], v[48:49], v[48:49], v[58:59]
	v_mul_f32_e32 v62, v57, v57
	v_pk_add_f32 v[60:61], v[88:89], v[58:59] op_sel_hi:[0,1]
	v_pk_fma_f32 v[60:61], v[56:57], v[56:57], v[60:61]
	v_lshlrev_b32_e32 v6, 16, v7
	v_and_b32_e32 v7, 0xffff0000, v7
	v_pk_add_f32 v[60:61], v[62:63], v[60:61] op_sel_hi:[0,1]
	v_pk_fma_f32 v[60:61], v[6:7], v[6:7], v[60:61]
	v_mul_f32_e32 v62, v7, v7
	v_lshlrev_b32_e32 v58, 16, v8
	v_and_b32_e32 v59, 0xffff0000, v8
	v_pk_add_f32 v[60:61], v[62:63], v[60:61] op_sel_hi:[0,1]
	v_pk_fma_f32 v[60:61], v[58:59], v[58:59], v[60:61]
	v_mul_f32_e32 v62, v59, v59
	v_lshlrev_b32_e32 v8, 16, v9
	v_and_b32_e32 v9, 0xffff0000, v9
	v_pk_add_f32 v[60:61], v[62:63], v[60:61] op_sel_hi:[0,1]
	v_pk_fma_f32 v[60:61], v[8:9], v[8:9], v[60:61]
	v_mul_f32_e32 v62, v9, v9
	v_pk_add_f32 v[66:67], v[62:63], v[60:61] op_sel_hi:[0,1]
	s_waitcnt vmcnt(1)
	v_lshlrev_b32_e32 v64, 16, v10
	v_and_b32_e32 v65, 0xffff0000, v10
	v_lshlrev_b32_e32 v62, 16, v11
	v_and_b32_e32 v63, 0xffff0000, v11
	v_lshlrev_b32_e32 v60, 16, v12
	v_and_b32_e32 v61, 0xffff0000, v12
	v_lshlrev_b32_e32 v10, 16, v13
	v_and_b32_e32 v11, 0xffff0000, v13
	v_pk_fma_f32 v[12:13], v[64:65], v[64:65], v[66:67]
	v_mul_f32_e32 v66, v65, v65
	v_pk_add_f32 v[12:13], v[66:67], v[12:13] op_sel_hi:[0,1]
	v_pk_fma_f32 v[12:13], v[62:63], v[62:63], v[12:13]
	v_mul_f32_e32 v66, v63, v63
	v_pk_add_f32 v[12:13], v[66:67], v[12:13] op_sel_hi:[0,1]
	v_pk_fma_f32 v[12:13], v[60:61], v[60:61], v[12:13]
	v_mul_f32_e32 v66, v61, v61
	v_pk_add_f32 v[12:13], v[66:67], v[12:13] op_sel_hi:[0,1]
	v_pk_fma_f32 v[12:13], v[10:11], v[10:11], v[12:13]
	v_mul_f32_e32 v66, v11, v11
	v_pk_add_f32 v[68:69], v[66:67], v[12:13] op_sel_hi:[0,1]
	s_waitcnt vmcnt(0)
	v_lshlrev_b32_e32 v66, 16, v14
	v_and_b32_e32 v67, 0xffff0000, v14
	v_pk_fma_f32 v[68:69], v[66:67], v[66:67], v[68:69]
	v_mul_f32_e32 v70, v67, v67
	v_lshlrev_b32_e32 v12, 16, v15
	v_and_b32_e32 v13, 0xffff0000, v15
	v_pk_add_f32 v[68:69], v[70:71], v[68:69] op_sel_hi:[0,1]
	v_pk_fma_f32 v[68:69], v[12:13], v[12:13], v[68:69]
	v_mul_f32_e32 v70, v13, v13
	v_lshlrev_b32_e32 v14, 16, v16
	v_and_b32_e32 v15, 0xffff0000, v16
	v_pk_add_f32 v[68:69], v[70:71], v[68:69] op_sel_hi:[0,1]
	v_pk_fma_f32 v[68:69], v[14:15], v[14:15], v[68:69]
	v_mul_f32_e32 v70, v15, v15
	v_lshlrev_b32_e32 v16, 16, v17
	v_and_b32_e32 v17, 0xffff0000, v17
	v_pk_add_f32 v[68:69], v[70:71], v[68:69] op_sel_hi:[0,1]
	v_pk_fma_f32 v[68:69], v[16:17], v[16:17], v[68:69]
	v_mul_f32_e32 v70, v17, v17
	v_pk_add_f32 v[68:69], v[70:71], v[68:69] op_sel_hi:[0,1]
	v_mov_b32_e32 v69, v68
	s_nop 1
	v_permlane32_swap_b32_e32 v68, v69
	s_cbranch_scc1 .LBB0_857
; __device__ __forceinline__ unsigned cvtpk(float lo, float hi) { const f32x2_t v = {lo, hi}; const bf16x2_t b = __builtin_convertvector(v, bf16x2_t); return __builtin_bit_cast(unsigned, b); }
; template <int MODE, bool FIXED>
; __device__ __forceinline__ void attn_unit(LAS unsigned char* lds, unsigned char* ws, const AttnParams& P, int l, int Tp, int sq, int h, int qb, int part, int np, int pslot, int tid, int wave, int lane) {
;     ...
;             const float rs = MODE ? (1.0f / sqrtf(ss * (1.0f / 64.0f) + NORM_EPS)) * (0.125f * LOG2E) : (1.0f / sqrtf(ss * (1.0f / 128.0f) + NORM_EPS)) * (0.08838834764831845f * LOG2E);
; #pragma unroll
;             for (int d0 = 0; d0 < NDD; ++d0) { const float* g = P.q_gain + d0 * 16 + hi * 8;
;                 const f32x4 ga = *(const f32x4*)g, gb = *(const f32x4*)(g + 4);
;                 v4u w; w.x = cvtpk(qf[d0][0] * rs * ga.x, qf[d0][1] * rs * ga.y); w.y = cvtpk(qf[d0][2] * rs * ga.z, qf[d0][3] * rs * ga.w);
;                 w.z = cvtpk(qf[d0][4] * rs * gb.x, qf[d0][5] * rs * gb.y); w.w = cvtpk(qf[d0][6] * rs * gb.z, qf[d0][7] * rs * gb.w);
;                 qr[d0] = __builtin_bit_cast(bf16x8, w); }
;         }
;         float m_reg = (MODE == 0) ? P.sink[h] * LOG2E : -1e30f; l_reg = (MODE == 0) ? (FIXED ? exp2f(P.sink[h] * LOG2E) : 1.f) : 0.f;
	v_sub_u32_e32 v70, v195, v135
	v_lshlrev_b32_e32 v181, 4, v193
	v_add_u32_e32 v73, s44, v70
	v_lshlrev_b32_e32 v70, 3, v193
	v_and_b32_e32 v71, 0xc0, v181
	v_lshlrev_b32_e32 v74, 1, v193
	v_and_or_b32 v71, v70, 24, v71
	v_and_b32_e32 v74, 32, v74
	v_and_b32_e32 v70, 0x100, v70
	v_ashrrev_i32_e32 v135, 4, v192
	v_or3_b32 v110, v71, v74, v70
	v_and_b32_e32 v74, 0xfffff0, v135
	v_lshlrev_b32_e32 v75, 1, v135
	v_lshlrev_b32_e32 v70, 3, v192
	v_and_or_b32 v74, v75, 8, v74
	v_lshrrev_b32_e32 v83, 1, v74
	v_bfe_u32 v90, v70, 5, 2
	v_and_b32_e32 v71, 0x78, v70
	v_or_b32_e32 v70, v83, v90
	v_lshrrev_b32_e32 v82, 1, v135
	v_lshlrev_b32_e32 v83, 9, v70
	v_and_b32_e32 v70, 3, v135
	v_and_or_b32 v70, v82, 4, v70
	v_lshlrev_b32_e32 v91, 6, v70
	v_lshlrev_b32_e32 v70, 1, v71
	s_mul_i32 s7, s12, 0x8600
	v_and_b32_e32 v71, 48, v70
	v_add_u32_e32 v146, 32, v135
	s_mul_hi_i32 s6, s12, 0x8600
	s_add_u32 s7, s50, s7
	v_or3_b32 v196, v83, v91, v71
	v_and_b32_e32 v82, 0xfffff0, v146
	v_lshlrev_b32_e32 v83, 1, v146
	s_addc_u32 s10, s51, s6
	s_lshl_b32 s6, s15, 1
	v_and_or_b32 v92, v83, 8, v82
	s_add_u32 s6, s7, s6
	v_lshrrev_b32_e32 v92, 1, v92
	s_addc_u32 s7, s10, 0
	s_lshl_b32 s10, s18, 2
	v_or_b32_e32 v90, v92, v90
	v_mov_b32_e32 v75, s10
	v_readlane_b32 s10, v254, 42
	v_lshlrev_b32_e32 v90, 9, v90
	v_readlane_b32 s11, v254, 43
	v_or3_b32 v197, v90, v91, v71
	v_mov_b32_e32 v71, v4
	v_lshl_add_u64 v[90:91], s[6:7], 0, v[70:71]
	s_mov_b64 s[6:7], 0x2a00
	v_lshlrev_b32_e32 v5, 2, v5
	global_load_dword v111, v75, s[10:11]
	v_readlane_b32 s10, v254, 44
	v_readlane_b32 s11, v254, 45
	v_lshl_add_u64 v[136:137], v[90:91], 0, s[6:7]
	s_mov_b64 s[6:7], 0x2800
	s_nop 2
	global_load_dwordx4 v[74:77], v5, s[10:11] offset:464
	global_load_dwordx4 v[78:81], v5, s[10:11] offset:448
	global_load_dwordx4 v[82:85], v5, s[10:11] offset:400
	global_load_dwordx4 v[86:89], v5, s[10:11] offset:384
	v_lshl_add_u64 v[172:173], v[90:91], 0, s[6:7]
	global_load_dwordx4 v[90:93], v5, s[10:11] offset:336
	global_load_dwordx4 v[94:97], v5, s[10:11] offset:320
	v_add_f32_e32 v68, v68, v69
	v_fmamk_f32 v68, v68, 0x3c000000, v220
	v_lshlrev_b32_e32 v71, 8, v135
	v_and_b32_e32 v98, 0x70, v192
	v_mul_f32_e32 v69, 0x4f800000, v68
	v_cmp_gt_f32_e32 vcc, s33, v68
	v_bitop3_b32 v207, v70, v71, v98 bitop3:0xde
	v_lshlrev_b32_e32 v71, 8, v146
	v_cndmask_b32_e32 v112, v68, v69, vcc
	v_bitop3_b32 v208, v70, v71, v98 bitop3:0xde
	v_sqrt_f32_e32 v102, v112
	global_load_dwordx4 v[68:71], v5, s[10:11] offset:272
	global_load_dwordx4 v[98:101], v5, s[10:11] offset:256
	v_mul_f32_e32 v176, 0xbfb8aa3b, v72
	s_add_i32 s6, 0, 0x4000
	v_add_u32_e32 v72, -1, v102
	v_cvt_f32_i32_e32 v177, v73
	v_fma_f32 v73, -v72, v102, v112
	v_add_u32_e32 v175, s6, v110
	v_cmp_ge_f32_e64 s[6:7], 0, v73
	v_add_u32_e32 v73, 1, v102
	v_add_u32_e32 v178, 0, v110
	v_cndmask_b32_e64 v72, v102, v72, s[6:7]
	v_fma_f32 v102, -v73, v102, v112
	v_cmp_lt_f32_e64 s[6:7], 0, v102
	global_load_dwordx4 v[102:105], v5, s[10:11] offset:208
	global_load_dwordx4 v[106:109], v5, s[10:11] offset:192
	v_cndmask_b32_e64 v72, v72, v73, s[6:7]
	v_mul_f32_e32 v73, 0x37800000, v72
	v_cndmask_b32_e32 v72, v72, v73, vcc
	v_cmp_class_f32_e32 vcc, v112, v221
	s_lshl_b32 s77, s14, 6
	s_add_i32 s73, s44, 0xffffff80
	v_cndmask_b32_e32 v72, v72, v112, vcc
	v_div_scale_f32 v73, s[6:7], v72, v72, 1.0
	v_rcp_f32_e32 v112, v73
	s_add_i32 s76, s44, 0x9f
	v_mov_b32_e32 v209, 1.0
	v_lshl_add_u32 v180, v195, 8, 0
	v_fma_f32 v110, -v73, v112, 1.0
	v_fmac_f32_e32 v112, v110, v112
	v_div_scale_f32 v110, vcc, 1.0, v72, 1.0
	v_mul_f32_e32 v113, v110, v112
	v_fma_f32 v114, -v73, v113, v110
	v_fmac_f32_e32 v113, v114, v112
	v_fma_f32 v73, -v73, v113, v110
	v_div_fmas_f32 v73, v73, v112, v113
	v_div_fixup_f32 v72, v73, v72, 1.0
	v_mul_f32_e32 v182, 0x3e0293ee, v72
	v_pk_mul_f32 v[12:13], v[182:183], v[12:13] op_sel_hi:[0,1]
	v_pk_mul_f32 v[6:7], v[182:183], v[6:7] op_sel_hi:[0,1]
	v_pk_mul_f32 v[66:67], v[182:183], v[66:67] op_sel_hi:[0,1]
	v_pk_mul_f32 v[10:11], v[182:183], v[10:11] op_sel_hi:[0,1]
	v_pk_mul_f32 v[2:3], v[182:183], v[2:3] op_sel_hi:[0,1]
	s_add_i32 s80, s14, 2
	v_add_u32_e32 v205, 0, v196
	v_add_u32_e32 v206, 0, v197
	v_add_u32_e32 v207, 0, v207
	v_add_u32_e32 v208, 0, v208
	s_mov_b32 s81, s14
	s_waitcnt vmcnt(10)
	v_mul_f32_e32 v179, 0x3fb8aa3b, v111
	global_load_dwordx4 v[110:113], v5, s[10:11] offset:144
	global_load_dwordx4 v[142:145], v5, s[10:11] offset:128
	s_waitcnt vmcnt(10)
	v_pk_mul_f32 v[12:13], v[12:13], v[80:81]
	s_nop 0
	v_cvt_pk_bf16_f32 v115, v12, v13
	v_pk_mul_f32 v[12:13], v[182:183], v[14:15] op_sel_hi:[0,1]
	s_waitcnt vmcnt(6)
	v_pk_mul_f32 v[6:7], v[6:7], v[96:97]
	v_pk_mul_f32 v[12:13], v[12:13], v[74:75]
	v_cvt_pk_bf16_f32 v123, v6, v7
	v_pk_mul_f32 v[6:7], v[182:183], v[58:59] op_sel_hi:[0,1]
	v_pk_mul_f32 v[6:7], v[6:7], v[90:91]
	v_cvt_pk_bf16_f32 v116, v12, v13
	v_pk_mul_f32 v[12:13], v[182:183], v[16:17] op_sel_hi:[0,1]
	v_cvt_pk_bf16_f32 v124, v6, v7
	v_pk_mul_f32 v[6:7], v[182:183], v[8:9] op_sel_hi:[0,1]
	v_pk_mul_f32 v[16:17], v[12:13], v[76:77]
	v_pk_mul_f32 v[6:7], v[6:7], v[92:93]
	v_cvt_pk_bf16_f32 v117, v16, v17
	v_pk_mul_f32 v[16:17], v[182:183], v[64:65] op_sel_hi:[0,1]
	v_cvt_pk_bf16_f32 v125, v6, v7
	v_pk_mul_f32 v[6:7], v[182:183], v[54:55] op_sel_hi:[0,1]
	v_pk_mul_f32 v[16:17], v[16:17], v[86:87]
	s_waitcnt vmcnt(4)
; __device__ __forceinline__ unsigned cvtpk(float lo, float hi) { const f32x2_t v = {lo, hi}; const bf16x2_t b = __builtin_convertvector(v, bf16x2_t); return __builtin_bit_cast(unsigned, b); }
; template <int MODE, bool FIXED>
; __device__ __forceinline__ void attn_unit(LAS unsigned char* lds, unsigned char* ws, const AttnParams& P, int l, int Tp, int sq, int h, int qb, int part, int np, int pslot, int tid, int wave, int lane) {
;     ...
;             for (int d0 = 0; d0 < NDD; ++d0) { const float* g = P.q_gain + d0 * 16 + hi * 8;
;                 const f32x4 ga = *(const f32x4*)g, gb = *(const f32x4*)(g + 4);
;                 v4u w; w.x = cvtpk(qf[d0][0] * rs * ga.x, qf[d0][1] * rs * ga.y); w.y = cvtpk(qf[d0][2] * rs * ga.z, qf[d0][3] * rs * ga.w);
;                 w.z = cvtpk(qf[d0][4] * rs * gb.x, qf[d0][5] * rs * gb.y); w.w = cvtpk(qf[d0][6] * rs * gb.z, qf[d0][7] * rs * gb.w);
;                 qr[d0] = __builtin_bit_cast(bf16x8, w); }
;         }
;         float m_reg = (MODE == 0) ? P.sink[h] * LOG2E : -1e30f; l_reg = (MODE == 0) ? (FIXED ? exp2f(P.sink[h] * LOG2E) : 1.f) : 0.f;
; #pragma unroll
;         for (int d = 0; d < 4; ++d)
; #pragma unroll
;             for (int r = 0; r < 16; ++r) o[d][r] = 0.f;
;         const bf16* Vg = PROJ + (size_t)seq0 * LDP + vcol + sc;
;         const bf16* Kg = MODE ? PROJ + (size_t)(seq0 + kr1) * LDP + kcol + mp * 64 + kc1 : PROJ + (size_t)seq0 * LDP + kcol + sc;
;         constexpr int DEPTH = 1;
;         struct Stg { v4u vs0, vs1, ks0, ks1; };
;         Stg sA, sB;
	v_pk_mul_f32 v[6:7], v[6:7], v[98:99]
	v_cvt_pk_bf16_f32 v118, v16, v17
	v_pk_mul_f32 v[16:17], v[182:183], v[62:63] op_sel_hi:[0,1]
	v_cvt_pk_bf16_f32 v126, v6, v7
	v_pk_mul_f32 v[6:7], v[182:183], v[52:53] op_sel_hi:[0,1]
	v_pk_mul_f32 v[66:67], v[66:67], v[78:79]
	global_load_dwordx4 v[12:15], v5, s[10:11] offset:80
	global_load_dwordx4 v[72:75], v5, s[10:11] offset:64
	v_pk_mul_f32 v[16:17], v[16:17], v[88:89]
	v_pk_mul_f32 v[6:7], v[6:7], v[100:101]
	v_cvt_pk_bf16_f32 v114, v66, v67
	v_cvt_pk_bf16_f32 v119, v16, v17
	v_pk_mul_f32 v[16:17], v[182:183], v[60:61] op_sel_hi:[0,1]
	global_load_dwordx4 v[60:63], v5, s[10:11] offset:16
	global_load_dwordx4 v[64:67], v5, s[10:11]
	v_cvt_pk_bf16_f32 v127, v6, v7
	v_pk_mul_f32 v[6:7], v[182:183], v[50:51] op_sel_hi:[0,1]
	v_pk_mul_f32 v[6:7], v[6:7], v[68:69]
	v_pk_mul_f32 v[10:11], v[10:11], v[84:85]
	v_cvt_pk_bf16_f32 v128, v6, v7
	v_pk_mul_f32 v[6:7], v[182:183], v[48:49] op_sel_hi:[0,1]
	v_pk_mul_f32 v[6:7], v[6:7], v[70:71]
	v_cvt_pk_bf16_f32 v121, v10, v11
	v_cvt_pk_bf16_f32 v129, v6, v7
	v_pk_mul_f32 v[6:7], v[182:183], v[46:47] op_sel_hi:[0,1]
	s_waitcnt vmcnt(6)
	v_pk_mul_f32 v[6:7], v[6:7], v[106:107]
	v_pk_mul_f32 v[10:11], v[182:183], v[56:57] op_sel_hi:[0,1]
	v_cvt_pk_bf16_f32 v130, v6, v7
	v_pk_mul_f32 v[6:7], v[182:183], v[44:45] op_sel_hi:[0,1]
	v_pk_mul_f32 v[6:7], v[6:7], v[108:109]
	v_add_u32_e32 v5, s77, v135
	v_cvt_pk_bf16_f32 v131, v6, v7
	v_pk_mul_f32 v[6:7], v[182:183], v[42:43] op_sel_hi:[0,1]
	v_pk_mul_f32 v[6:7], v[6:7], v[102:103]
	v_pk_mul_f32 v[16:17], v[16:17], v[82:83]
	v_cvt_pk_bf16_f32 v132, v6, v7
	v_pk_mul_f32 v[6:7], v[182:183], v[40:41] op_sel_hi:[0,1]
	v_pk_mul_f32 v[6:7], v[6:7], v[104:105]
	v_pk_mul_f32 v[10:11], v[10:11], v[94:95]
	v_cvt_pk_bf16_f32 v133, v6, v7
	v_mad_i64_i32 v[6:7], s[6:7], v5, s70, v[136:137]
	v_mad_i64_i32 v[8:9], s[6:7], v5, s70, v[172:173]
	v_add_u32_e32 v5, s77, v146
	v_cvt_pk_bf16_f32 v120, v16, v17
	v_cvt_pk_bf16_f32 v122, v10, v11
	v_mad_i64_i32 v[10:11], s[6:7], v5, s70, v[172:173]
	v_mad_i64_i32 v[16:17], s[6:7], v5, s70, v[136:137]
	global_load_dwordx4 v[146:149], v[6:7], off
	global_load_dwordx4 v[158:161], v[8:9], off
	global_load_dwordx4 v[154:157], v[16:17], off
	global_load_dwordx4 v[162:165], v[10:11], off
	v_pk_mul_f32 v[6:7], v[182:183], v[32:33] op_sel_hi:[0,1]
	s_movk_i32 s6, 0x70
	v_mov_b32_e32 v16, v4
	v_mov_b32_e32 v17, v4
	v_mov_b32_e32 v5, v4
	v_mov_b32_e32 v8, v4
	v_mov_b32_e32 v9, v4
	s_waitcnt vmcnt(8)
	v_pk_mul_f32 v[6:7], v[6:7], v[142:143]
	v_mov_b32_e32 v10, v4
	v_cvt_pk_bf16_f32 v142, v6, v7
	v_pk_mul_f32 v[6:7], v[182:183], v[28:29] op_sel_hi:[0,1]
	v_pk_mul_f32 v[6:7], v[6:7], v[144:145]
	v_mov_b32_e32 v11, v4
	v_cvt_pk_bf16_f32 v143, v6, v7
	v_pk_mul_f32 v[6:7], v[182:183], v[26:27] op_sel_hi:[0,1]
	v_pk_mul_f32 v[6:7], v[6:7], v[110:111]
	s_waitcnt vmcnt(7)
	v_pk_mul_f32 v[2:3], v[2:3], v[14:15]
	s_nop 0
	v_cvt_pk_bf16_f32 v153, v2, v3
	v_pk_mul_f32 v[2:3], v[182:183], v[38:39] op_sel_hi:[0,1]
	v_cvt_pk_bf16_f32 v144, v6, v7
	v_pk_mul_f32 v[6:7], v[182:183], v[24:25] op_sel_hi:[0,1]
	v_pk_mul_f32 v[6:7], v[6:7], v[112:113]
	v_mov_b32_e32 v14, v4
	s_waitcnt vmcnt(4)
	v_pk_mul_f32 v[2:3], v[2:3], v[64:65]
	v_cvt_pk_bf16_f32 v145, v6, v7
	v_cvt_pk_bf16_f32 v166, v2, v3
	v_pk_mul_f32 v[2:3], v[182:183], v[36:37] op_sel_hi:[0,1]
	v_pk_mul_f32 v[2:3], v[2:3], v[66:67]
	v_pk_mul_f32 v[6:7], v[182:183], v[22:23] op_sel_hi:[0,1]
	v_cvt_pk_bf16_f32 v167, v2, v3
	v_pk_mul_f32 v[2:3], v[182:183], v[34:35] op_sel_hi:[0,1]
	v_pk_mul_f32 v[2:3], v[2:3], v[60:61]
	v_pk_mul_f32 v[6:7], v[6:7], v[72:73]
	v_cvt_pk_bf16_f32 v168, v2, v3
	v_pk_mul_f32 v[2:3], v[182:183], v[30:31] op_sel_hi:[0,1]
	v_pk_mul_f32 v[2:3], v[2:3], v[62:63]
	v_cvt_pk_bf16_f32 v150, v6, v7
	v_cvt_pk_bf16_f32 v169, v2, v3
	v_and_b32_e32 v3, 0x70, v181
	v_bitop3_b32 v181, v170, v181, s6 bitop3:0x78
	s_movk_i32 s6, 0x60
	v_bitop3_b32 v187, v170, v3, s6 bitop3:0x36
	s_movk_i32 s6, 0x80
	v_pk_mul_f32 v[6:7], v[182:183], v[20:21] op_sel_hi:[0,1]
	v_bitop3_b32 v189, v170, v3, s6 bitop3:0x36
	s_movk_i32 s6, 0xa0
	v_pk_mul_f32 v[6:7], v[6:7], v[74:75]
	v_bitop3_b32 v191, v170, v3, s6 bitop3:0x36
	s_movk_i32 s6, 0xc0
	v_cvt_pk_bf16_f32 v151, v6, v7
	v_pk_mul_f32 v[6:7], v[182:183], v[18:19] op_sel_hi:[0,1]
	v_bitop3_b32 v201, v170, v3, s6 bitop3:0x36
	s_movk_i32 s6, 0xe0
	v_pk_mul_f32 v[6:7], v[6:7], v[12:13]
	v_lshlrev_b32_e32 v2, 8, v193
	v_bitop3_b32 v183, v170, v3, 32 bitop3:0x36
	v_bitop3_b32 v185, v170, v3, 64 bitop3:0x36
	v_bitop3_b32 v203, v170, v3, s6 bitop3:0x36
	v_cvt_pk_bf16_f32 v152, v6, v7
	v_or3_b32 v182, v2, v181, s3
	v_or3_b32 v184, v2, v183, s3
	v_or3_b32 v186, v2, v185, s3
	v_or3_b32 v188, v2, v187, s3
	v_or3_b32 v190, v2, v189, s3
	v_or3_b32 v200, v2, v191, s3
	v_or3_b32 v202, v2, v201, s3
	v_or3_b32 v204, v2, v203, s3
	v_mov_b32_e32 v2, v4
	v_mov_b32_e32 v3, v4
	v_mov_b32_e32 v6, v4
	v_mov_b32_e32 v7, v4
	v_mov_b32_e32 v12, v4
	v_mov_b32_e32 v13, v4
	v_mov_b32_e32 v15, v4
	v_mov_b64_e32 v[80:81], v[16:17]
	v_mov_b64_e32 v[64:65], v[16:17]
	v_mov_b64_e32 v[48:49], v[16:17]
	v_mov_b64_e32 v[32:33], v[16:17]
	v_mov_b64_e32 v[78:79], v[14:15]
	v_mov_b64_e32 v[76:77], v[12:13]
	v_mov_b64_e32 v[74:75], v[10:11]
	v_mov_b64_e32 v[72:73], v[8:9]
	v_mov_b64_e32 v[70:71], v[6:7]
	v_mov_b64_e32 v[68:69], v[4:5]
	v_mov_b64_e32 v[66:67], v[2:3]
	v_mov_b64_e32 v[62:63], v[14:15]
	v_mov_b64_e32 v[60:61], v[12:13]
	v_mov_b64_e32 v[58:59], v[10:11]
	v_mov_b64_e32 v[56:57], v[8:9]
	v_mov_b64_e32 v[54:55], v[6:7]
	v_mov_b64_e32 v[52:53], v[4:5]
	v_mov_b64_e32 v[50:51], v[2:3]
	v_mov_b64_e32 v[46:47], v[14:15]
	v_mov_b64_e32 v[44:45], v[12:13]
	v_mov_b64_e32 v[42:43], v[10:11]
	v_mov_b64_e32 v[40:41], v[8:9]
	v_mov_b64_e32 v[38:39], v[6:7]
	v_mov_b64_e32 v[36:37], v[4:5]
	v_mov_b64_e32 v[34:35], v[2:3]
	v_mov_b64_e32 v[30:31], v[14:15]
	v_mov_b64_e32 v[28:29], v[12:13]
	v_mov_b64_e32 v[26:27], v[10:11]
	v_mov_b64_e32 v[24:25], v[8:9]
	v_mov_b64_e32 v[22:23], v[6:7]
	v_mov_b64_e32 v[20:21], v[4:5]
	v_mov_b64_e32 v[18:19], v[2:3]

; #define LAS __attribute__((address_space(3)))
; __device__ __forceinline__ unsigned cvtpk(float lo, float hi) { const f32x2_t v = {lo, hi}; const bf16x2_t b = __builtin_convertvector(v, bf16x2_t); return __builtin_bit_cast(unsigned, b); }
; #define SLOAD(S, k0) do { S.vs0 = *(const v4u*)(Vg + (size_t)((k0) + sr) * LDP); S.vs1 = *(const v4u*)(Vg + (size_t)((k0) + 32 + sr) * LDP); \
;         if (MODE) { S.ks0 = *(const v4u*)(Kg + (size_t)(k0) * LDP); } \
;         else { S.ks0 = *(const v4u*)(Kg + (size_t)((k0) + sr) * LDP); S.ks1 = *(const v4u*)(Kg + (size_t)((k0) + 32 + sr) * LDP); } } while (0)
; template <int MODE, bool FIXED>
; __device__ __forceinline__ void attn_unit(LAS unsigned char* lds, unsigned char* ws, const AttnParams& P, int l, int Tp, int sq, int h, int qb, int part, int np, int pslot, int tid, int wave, int lane) {
;     ...
;         if (MODE == 1 && tid < 64) {
;             const unsigned one2 = 0x3F803F80u, cw = cvtpk((float)tid, (float)tid);
;             *(LAS v4u*)(K_lds + 8192 + tid * 32) = (v4u){one2, cw, 0u, 0u}; *(LAS v4u*)(K_lds + 8192 + tid * 32 + 16) = (v4u){0u, 0u, 0u, 0u}; }
;         if (jlo < jhi) SLOAD(sA, jlo * 64);
.LBB0_931:
	s_or_b64 exec, exec, s[10:11]
	s_lshl_b32 s10, s26, 6
	s_lshl_b32 s60, s10, 1
	v_lshl_add_u64 v[186:187], v[174:175], 0, s[60:61]
	s_and_saveexec_b64 s[10:11], s[8:9]
	s_cbranch_execz .LBB0_933
	v_readfirstlane_b32 s100, v168
	v_readfirstlane_b32 s101, v188
	s_mov_b32 s53, 0
	s_add_i32 s101, s101, -1
	v_and_b32_e32 v113, 63, v0
	v_bfe_u32 v110, v113, 2, 3
	v_and_b32_e32 v111, 3, v110
	v_lshrrev_b32_e32 v110, 2, v110
	v_lshl_or_b32 v110, v110, 3, v111
	s_lshr_b32 s3, s31, 1
	s_lshl_b32 s3, s3, 4
	s_and_b32 s73, s31, 1
	s_lshl_b32 s73, s73, 2
	s_add_i32 s3, s3, s73
	v_add_u32_e32 v110, s3, v110
	v_and_b32_e32 v111, 15, v0
	v_lshlrev_b32_e32 v111, 4, v111
	v_sub_co_u32_e64 v108, s[98:99], v172, v111
	s_nop 1
	v_subbrev_co_u32_e64 v109, s[98:99], 0, v173, s[98:99]
	v_mad_i64_i32 v[102:103], s[98:99], v110, s70, v[108:109]
	v_and_b32_e32 v111, 3, v113
	v_lshlrev_b32_e32 v111, 4, v111
	v_lshrrev_b32_e32 v110, 5, v113
	v_lshl_or_b32 v110, v110, 6, v111
	v_mov_b32_e32 v111, 0
	v_lshl_add_u64 v[102:103], v[102:103], 0, v[110:111]
	v_and_b32_e32 v110, 7, v0
	v_lshlrev_b32_e32 v110, 4, v110
	v_bfe_u32 v112, v0, 4, 3
	v_lshlrev_b32_e32 v112, 4, v112
	v_xor_b32_e32 v112, v110, v112
	v_sub_co_u32_e64 v104, s[98:99], v186, v110
	s_nop 1
	v_subbrev_co_u32_e64 v105, s[98:99], 0, v187, s[98:99]
	v_mov_b32_e32 v113, 0
	v_lshl_add_u64 v[104:105], v[104:105], 0, v[112:113]
	v_and_b32_e32 v113, 31, v0
	v_cvt_f32_u32_e32 v112, v113
	v_add_u32_e32 v113, 32, v113
	v_cvt_pk_bf16_f32 v111, v112, v112
	v_cvt_f32_u32_e32 v112, v113
	v_and_b32_e32 v113, 32, v0
	v_cvt_pk_bf16_f32 v177, v112, v112
	v_cmp_eq_u32_e64 s[98:99], 0, v113
	v_mov_b32_e32 v110, 0x3f803f80
	v_mov_b32_e32 v112, 0
	v_cndmask_b32_e64 v110, 0, v110, s[98:99]
	v_cndmask_b32_e64 v111, 0, v111, s[98:99]
	v_cndmask_b32_e64 v177, 0, v177, s[98:99]
	v_mov_b32_e32 v113, 0
	v_mov_b32_e32 v176, v110
	v_mov_b32_e32 v178, 0
	v_mov_b32_e32 v179, 0
	s_mov_b32 s99, 0
	s_min_i32 s3, s100, s101
	s_mul_i32 s98, s3, 0x218000
	s_lshl_b32 s73, s31, 11
	s_add_i32 s73, s73, s53
	s_mov_b32 m0, s73
	v_lshl_add_u64 v[106:107], v[102:103], 0, s[98:99]
	v_lshl_add_u64 v[108:109], v[104:105], 0, s[98:99]
	global_load_lds_dwordx4 v[106:107], off
	s_add_i32 m0, s73, 0x380
	s_lshl_b32 s3, s31, 10
	s_add_i32 s3, s3, s53
	global_load_lds_dwordx4 v[106:107], off offset:128
	s_add_i32 m0, s3, 0x10000
	s_add_i32 s100, s100, 1
	s_add_i32 s53, s53, 0x4000
	global_load_lds_dwordx4 v[108:109], off
	s_and_b32 s53, s53, 0xc000
	s_min_i32 s3, s100, s101
	s_mul_i32 s98, s3, 0x218000
	s_lshl_b32 s73, s31, 11
	s_add_i32 s73, s73, s53
	s_mov_b32 m0, s73
	v_lshl_add_u64 v[106:107], v[102:103], 0, s[98:99]
	v_lshl_add_u64 v[108:109], v[104:105], 0, s[98:99]
	global_load_lds_dwordx4 v[106:107], off
	s_add_i32 m0, s73, 0x380
	s_lshl_b32 s3, s31, 10
	s_add_i32 s3, s3, s53
	global_load_lds_dwordx4 v[106:107], off offset:128
	s_add_i32 m0, s3, 0x10000
	s_add_i32 s100, s100, 1
	s_add_i32 s53, s53, 0x4000
	global_load_lds_dwordx4 v[108:109], off
	s_and_b32 s53, s53, 0xc000
	s_min_i32 s3, s100, s101
	s_mul_i32 s98, s3, 0x218000
	s_lshl_b32 s73, s31, 11
	s_add_i32 s73, s73, s53
	s_mov_b32 m0, s73
	v_lshl_add_u64 v[106:107], v[102:103], 0, s[98:99]
	v_lshl_add_u64 v[108:109], v[104:105], 0, s[98:99]
	global_load_lds_dwordx4 v[106:107], off
	s_add_i32 m0, s73, 0x380
	s_lshl_b32 s3, s31, 10
	s_add_i32 s3, s3, s53
	global_load_lds_dwordx4 v[106:107], off offset:128
	s_add_i32 m0, s3, 0x10000
	s_add_i32 s100, s100, 1
	s_add_i32 s53, s53, 0x4000
	global_load_lds_dwordx4 v[108:109], off
	s_and_b32 s53, s53, 0xc000

; #define MFMA32(a, b, c) __builtin_amdgcn_mfma_f32_32x32x16_bf16((a), (b), (c), 0, 0, 0)
; #define SBAR() __builtin_amdgcn_sched_barrier(0)
; template <int D0> __device__ __forceinline__ void pv_one(f32x16& od, int vb, bf16x8 pa0, bf16x8 pa1, bf16x8 pa2, bf16x8 pa3) {
;     const s16x4 l0 = tr_read<v_rd_off(D0, 0, 0)>(vb), h0 = tr_read<v_rd_off(D0, 0, 1)>(vb), l1 = tr_read<v_rd_off(D0, 1, 0)>(vb), h1 = tr_read<v_rd_off(D0, 1, 1)>(vb);
;     const s16x4 l2 = tr_read<v_rd_off(D0, 2, 0)>(vb), h2 = tr_read<v_rd_off(D0, 2, 1)>(vb), l3 = tr_read<v_rd_off(D0, 3, 0)>(vb), h3 = tr_read<v_rd_off(D0, 3, 1)>(vb);
;     asm volatile("s_waitcnt lgkmcnt(0)" ::: "memory"); SBAR();
;     ...
;     od = MFMA32(pa0, PK(l0, h0), od); od = MFMA32(pa1, PK(l1, h1), od); od = MFMA32(pa2, PK(l2, h2), od); od = MFMA32(pa3, PK(l3, h3), od);
;     ...
; }
; __device__ __forceinline__ void pv_d0(f32x16* o, int vb, bf16x8 pa0, bf16x8 pa1, bf16x8 pa2, bf16x8 pa3) {
;     pv_one<0>(o[0], vb, pa0, pa1, pa2, pa3); pv_one<1>(o[1], vb, pa0, pa1, pa2, pa3); pv_one<2>(o[2], vb, pa0, pa1, pa2, pa3); pv_one<3>(o[3], vb, pa0, pa1, pa2, pa3);
; template <bool FIXED>
; __device__ __forceinline__ float softmax_tile(f32x16& p0, f32x16& p1, float& m_reg, float& l_reg, bf16x8& pa0, bf16x8& pa1, bf16x8& pa2, bf16x8& pa3) {
;     ...
; #pragma unroll
;         for (int r = 0; r < 16; ++r) { p0[r] = __builtin_amdgcn_exp2f(p0[r]); p1[r] = __builtin_amdgcn_exp2f(p1[r]); }
;     }
;     float ps = 0.f;
; #pragma unroll
;     for (int r = 0; r < 16; ++r) ps += p0[r];
; #pragma unroll
;     for (int r = 0; r < 16; ++r) ps += p1[r];
;     ps = half_sum(ps);
;     l_reg = l_reg * alpha + ps;
;     ...
;     PK4(p0, 0, pa0); PK4(p0, 8, pa1); PK4(p1, 0, pa2); PK4(p1, 8, pa3);
.Lattn_exp2:
	v_add_u32_e32 v5, s29, v200
	ds_read_b64_tr_b16 v[228:229], v5 offset:0
	ds_read_b64_tr_b16 v[230:231], v5 offset:2048
	ds_read_b64_tr_b16 v[240:241], v5 offset:512
	ds_read_b64_tr_b16 v[242:243], v5 offset:2560
	ds_read_b64_tr_b16 v[244:245], v5 offset:1024
	ds_read_b64_tr_b16 v[246:247], v5 offset:3072
	s_nop 2
	v_exp_f32_e32 v70, v70
	v_exp_f32_e32 v71, v71
	v_add_f32_e32 v2, 0, v70
	v_exp_f32_e32 v72, v72
	v_add_f32_e32 v2, v71, v2
	v_exp_f32_e32 v73, v73
	v_add_f32_e32 v2, v72, v2
	v_exp_f32_e32 v74, v74
	v_add_f32_e32 v2, v73, v2
	v_exp_f32_e32 v75, v75
	v_add_f32_e32 v2, v74, v2
	v_exp_f32_e32 v76, v76
	v_add_f32_e32 v2, v75, v2
	v_exp_f32_e32 v77, v77
	v_add_f32_e32 v2, v76, v2
	v_cvt_pk_bf16_f32 v70, v70, v71
	v_add_f32_e32 v2, v77, v2
	v_cvt_pk_bf16_f32 v71, v72, v73
	v_cvt_pk_bf16_f32 v72, v74, v75
	v_cvt_pk_bf16_f32 v73, v76, v77
	ds_read_b64_tr_b16 v[74:75], v5 offset:1536
	ds_read_b64_tr_b16 v[76:77], v5 offset:3584
	v_permlane32_swap_b32_e32 v70, v72
	v_permlane32_swap_b32_e32 v71, v73
	s_waitcnt lgkmcnt(6)
	s_nop 0
	v_mfma_f32_32x32x16_bf16 v[54:69], v[70:73], v[228:231], v[54:69]
	ds_read_b64_tr_b16 v[228:229], v5 offset:4096
	ds_read_b64_tr_b16 v[230:231], v5 offset:6144
	v_exp_f32_e32 v78, v78
	v_exp_f32_e32 v79, v79
	v_add_f32_e32 v2, v78, v2
	v_exp_f32_e32 v80, v80
	v_add_f32_e32 v2, v79, v2
	v_exp_f32_e32 v81, v81
	s_waitcnt lgkmcnt(6)
	v_mfma_f32_32x32x16_bf16 v[38:53], v[70:73], v[240:243], v[38:53]
	ds_read_b64_tr_b16 v[240:241], v5 offset:4608
	ds_read_b64_tr_b16 v[242:243], v5 offset:6656
	v_add_f32_e32 v2, v80, v2
	v_exp_f32_e32 v82, v82
	v_add_f32_e32 v2, v81, v2
	v_exp_f32_e32 v83, v83
	v_add_f32_e32 v2, v82, v2
	v_exp_f32_e32 v84, v84
	s_waitcnt lgkmcnt(6)
	v_mfma_f32_32x32x16_bf16 v[22:37], v[70:73], v[244:247], v[22:37]
	ds_read_b64_tr_b16 v[244:245], v5 offset:5120
	ds_read_b64_tr_b16 v[246:247], v5 offset:7168
	v_add_f32_e32 v2, v83, v2
	v_exp_f32_e32 v85, v85
	v_add_f32_e32 v2, v84, v2
	v_cvt_pk_bf16_f32 v78, v78, v79
	v_add_f32_e32 v2, v85, v2
	s_waitcnt lgkmcnt(6)
	v_mfma_f32_32x32x16_bf16 v[6:21], v[70:73], v[74:77], v[6:21]
	v_cvt_pk_bf16_f32 v79, v80, v81
	v_cvt_pk_bf16_f32 v80, v82, v83
	v_cvt_pk_bf16_f32 v81, v84, v85
	ds_read_b64_tr_b16 v[74:75], v5 offset:5632
	ds_read_b64_tr_b16 v[76:77], v5 offset:7680
	v_permlane32_swap_b32_e32 v78, v80
	v_permlane32_swap_b32_e32 v79, v81
	s_waitcnt lgkmcnt(6)
	s_nop 0
	v_mfma_f32_32x32x16_bf16 v[54:69], v[78:81], v[228:231], v[54:69]
	ds_read_b64_tr_b16 v[228:229], v5 offset:8192
	ds_read_b64_tr_b16 v[230:231], v5 offset:10240
	v_exp_f32_e32 v86, v86
	v_exp_f32_e32 v87, v87
	v_add_f32_e32 v2, v86, v2
	v_exp_f32_e32 v88, v88
	v_add_f32_e32 v2, v87, v2
	v_exp_f32_e32 v89, v89
	s_waitcnt lgkmcnt(6)
	v_mfma_f32_32x32x16_bf16 v[38:53], v[78:81], v[240:243], v[38:53]
	s_min_i32 s3, s100, s101
	s_mul_i32 s98, s3, 0x218000
	s_lshl_b32 s73, s31, 11
	s_add_i32 s73, s73, s53
	s_mov_b32 m0, s73
	v_lshl_add_u64 v[106:107], v[102:103], 0, s[98:99]
	v_lshl_add_u64 v[108:109], v[104:105], 0, s[98:99]
	global_load_lds_dwordx4 v[106:107], off
	ds_read_b64_tr_b16 v[240:241], v5 offset:8704
	ds_read_b64_tr_b16 v[242:243], v5 offset:10752
	v_add_f32_e32 v2, v88, v2
	v_exp_f32_e32 v90, v90
	v_add_f32_e32 v2, v89, v2
	v_exp_f32_e32 v91, v91
	v_add_f32_e32 v2, v90, v2
	v_exp_f32_e32 v92, v92
	s_waitcnt lgkmcnt(6)
	v_mfma_f32_32x32x16_bf16 v[22:37], v[78:81], v[244:247], v[22:37]
	ds_read_b64_tr_b16 v[244:245], v5 offset:9216
	ds_read_b64_tr_b16 v[246:247], v5 offset:11264
	v_add_f32_e32 v2, v91, v2
	v_exp_f32_e32 v93, v93
	v_add_f32_e32 v2, v92, v2
	v_cvt_pk_bf16_f32 v86, v86, v87
	v_add_f32_e32 v2, v93, v2
	s_waitcnt lgkmcnt(6)
	v_mfma_f32_32x32x16_bf16 v[6:21], v[78:81], v[74:77], v[6:21]
	v_cvt_pk_bf16_f32 v87, v88, v89
	v_cvt_pk_bf16_f32 v88, v90, v91
	v_cvt_pk_bf16_f32 v89, v92, v93
	ds_read_b64_tr_b16 v[74:75], v5 offset:9728
	ds_read_b64_tr_b16 v[76:77], v5 offset:11776
	v_permlane32_swap_b32_e32 v86, v88
	v_permlane32_swap_b32_e32 v87, v89
	s_waitcnt lgkmcnt(6)
	s_nop 0
	v_mfma_f32_32x32x16_bf16 v[54:69], v[86:89], v[228:231], v[54:69]
	ds_read_b64_tr_b16 v[228:229], v5 offset:12288
	ds_read_b64_tr_b16 v[230:231], v5 offset:14336
	v_exp_f32_e32 v94, v94
	v_exp_f32_e32 v95, v95
	v_add_f32_e32 v2, v94, v2
	v_exp_f32_e32 v96, v96
	v_add_f32_e32 v2, v95, v2
	v_exp_f32_e32 v97, v97
	s_waitcnt lgkmcnt(6)
	v_mfma_f32_32x32x16_bf16 v[38:53], v[86:89], v[240:243], v[38:53]
	s_add_i32 m0, s73, 0x380
	s_lshl_b32 s3, s31, 10
	s_add_i32 s3, s3, s53
	global_load_lds_dwordx4 v[106:107], off offset:128
	ds_read_b64_tr_b16 v[240:241], v5 offset:12800
	ds_read_b64_tr_b16 v[242:243], v5 offset:14848
	v_add_f32_e32 v2, v96, v2
	v_exp_f32_e32 v98, v98
	v_add_f32_e32 v2, v97, v2
	v_exp_f32_e32 v99, v99
	v_add_f32_e32 v2, v98, v2
	v_exp_f32_e32 v100, v100
	s_waitcnt lgkmcnt(6)
	v_mfma_f32_32x32x16_bf16 v[22:37], v[86:89], v[244:247], v[22:37]
	ds_read_b64_tr_b16 v[244:245], v5 offset:13312
	ds_read_b64_tr_b16 v[246:247], v5 offset:15360
	v_add_f32_e32 v2, v99, v2
	v_exp_f32_e32 v101, v101
	v_add_f32_e32 v2, v100, v2
	v_cvt_pk_bf16_f32 v94, v94, v95
	v_add_f32_e32 v2, v101, v2
	s_waitcnt lgkmcnt(6)
	v_mfma_f32_32x32x16_bf16 v[6:21], v[86:89], v[74:77], v[6:21]
	v_cvt_pk_bf16_f32 v95, v96, v97
	v_cvt_pk_bf16_f32 v96, v98, v99
	v_cvt_pk_bf16_f32 v97, v100, v101
	ds_read_b64_tr_b16 v[74:75], v5 offset:13824
	ds_read_b64_tr_b16 v[76:77], v5 offset:15872
	v_permlane32_swap_b32_e32 v94, v96
	v_permlane32_swap_b32_e32 v95, v97
	v_mov_b32_e32 v3, v2
	s_waitcnt lgkmcnt(6)
	s_nop 0
	v_mfma_f32_32x32x16_bf16 v[54:69], v[94:97], v[228:231], v[54:69]
	v_mov_b32_e32 v236, v238
	s_waitcnt lgkmcnt(4)
	v_mfma_f32_32x32x16_bf16 v[38:53], v[94:97], v[240:243], v[38:53]
	s_add_i32 m0, s3, 0x10000
	s_add_i32 s100, s100, 1
	s_add_i32 s53, s53, 0x4000
	global_load_lds_dwordx4 v[108:109], off
	s_and_b32 s53, s53, 0xc000
	v_permlane32_swap_b32_e32 v2, v3
	s_waitcnt lgkmcnt(2)
	v_mfma_f32_32x32x16_bf16 v[22:37], v[94:97], v[244:247], v[22:37]
	s_waitcnt lgkmcnt(0)
	v_mfma_f32_32x32x16_bf16 v[6:21], v[94:97], v[74:77], v[6:21]
	v_add_f32_e32 v2, v2, v3
	v_add_f32_e32 v219, v219, v2

; #define MFMA32(a, b, c) __builtin_amdgcn_mfma_f32_32x32x16_bf16((a), (b), (c), 0, 0, 0)
; #define SBAR() __builtin_amdgcn_sched_barrier(0)
; template <int D0> __device__ __forceinline__ void pv_one(f32x16& od, int vb, bf16x8 pa0, bf16x8 pa1, bf16x8 pa2, bf16x8 pa3) {
;     const s16x4 l0 = tr_read<v_rd_off(D0, 0, 0)>(vb), h0 = tr_read<v_rd_off(D0, 0, 1)>(vb), l1 = tr_read<v_rd_off(D0, 1, 0)>(vb), h1 = tr_read<v_rd_off(D0, 1, 1)>(vb);
;     const s16x4 l2 = tr_read<v_rd_off(D0, 2, 0)>(vb), h2 = tr_read<v_rd_off(D0, 2, 1)>(vb), l3 = tr_read<v_rd_off(D0, 3, 0)>(vb), h3 = tr_read<v_rd_off(D0, 3, 1)>(vb);
;     asm volatile("s_waitcnt lgkmcnt(0)" ::: "memory"); SBAR();
;     ...
;     od = MFMA32(pa0, PK(l0, h0), od); od = MFMA32(pa1, PK(l1, h1), od); od = MFMA32(pa2, PK(l2, h2), od); od = MFMA32(pa3, PK(l3, h3), od);
;     ...
; }
; __device__ __forceinline__ void pv_d0(f32x16* o, int vb, bf16x8 pa0, bf16x8 pa1, bf16x8 pa2, bf16x8 pa3) {
;     pv_one<0>(o[0], vb, pa0, pa1, pa2, pa3); pv_one<1>(o[1], vb, pa0, pa1, pa2, pa3); pv_one<2>(o[2], vb, pa0, pa1, pa2, pa3); pv_one<3>(o[3], vb, pa0, pa1, pa2, pa3);
; template <bool FIXED>
; __device__ __forceinline__ float softmax_tile(f32x16& p0, f32x16& p1, float& m_reg, float& l_reg, bf16x8& pa0, bf16x8& pa1, bf16x8& pa2, bf16x8& pa3) {
;     ...
;         for (int r = 0; r < 16; ++r) { p0[r] = __builtin_amdgcn_exp2f(p0[r] - mn); p1[r] = __builtin_amdgcn_exp2f(p1[r] - mn); }
;     } else {
; #pragma unroll
;         for (int r = 0; r < 16; ++r) { p0[r] = __builtin_amdgcn_exp2f(p0[r]); p1[r] = __builtin_amdgcn_exp2f(p1[r]); }
;     }
;     float ps = 0.f;
; #pragma unroll
;     for (int r = 0; r < 16; ++r) ps += p0[r];
; #pragma unroll
;     for (int r = 0; r < 16; ++r) ps += p1[r];
;     ps = half_sum(ps);
;     l_reg = l_reg * alpha + ps;
;     ...
;     PK4(p0, 0, pa0); PK4(p0, 8, pa1); PK4(p1, 0, pa2); PK4(p1, 8, pa3);
.Lattn_exp1:
	v_add_u32_e32 v5, s29, v200
	ds_read_b64_tr_b16 v[228:229], v5 offset:0
	ds_read_b64_tr_b16 v[230:231], v5 offset:2048
	ds_read_b64_tr_b16 v[240:241], v5 offset:512
	ds_read_b64_tr_b16 v[242:243], v5 offset:2560
	ds_read_b64_tr_b16 v[244:245], v5 offset:1024
	ds_read_b64_tr_b16 v[246:247], v5 offset:3072
	s_nop 2
	v_exp_f32_e32 v70, v70
	v_exp_f32_e32 v71, v71
	v_add_f32_e32 v2, 0, v70
	v_exp_f32_e32 v72, v72
	v_add_f32_e32 v2, v71, v2
	v_exp_f32_e32 v73, v73
	v_add_f32_e32 v2, v72, v2
	v_exp_f32_e32 v74, v74
	v_add_f32_e32 v2, v73, v2
	v_exp_f32_e32 v75, v75
	v_add_f32_e32 v2, v74, v2
	v_exp_f32_e32 v76, v76
	v_add_f32_e32 v2, v75, v2
	v_exp_f32_e32 v77, v77
	v_add_f32_e32 v2, v76, v2
	v_cvt_pk_bf16_f32 v70, v70, v71
	v_add_f32_e32 v2, v77, v2
	v_cvt_pk_bf16_f32 v71, v72, v73
	v_cvt_pk_bf16_f32 v72, v74, v75
	v_cvt_pk_bf16_f32 v73, v76, v77
	ds_read_b64_tr_b16 v[74:75], v5 offset:1536
	ds_read_b64_tr_b16 v[76:77], v5 offset:3584
	v_permlane32_swap_b32_e32 v70, v72
	v_permlane32_swap_b32_e32 v71, v73
	s_waitcnt lgkmcnt(6)
	s_nop 0
	v_mfma_f32_32x32x16_bf16 v[54:69], v[70:73], v[228:231], v[54:69]
	ds_read_b64_tr_b16 v[228:229], v5 offset:4096
	ds_read_b64_tr_b16 v[230:231], v5 offset:6144
	v_exp_f32_e32 v78, v78
	v_exp_f32_e32 v79, v79
	v_add_f32_e32 v2, v78, v2
	v_exp_f32_e32 v80, v80
	v_add_f32_e32 v2, v79, v2
	v_exp_f32_e32 v81, v81
	s_waitcnt lgkmcnt(6)
	v_mfma_f32_32x32x16_bf16 v[38:53], v[70:73], v[240:243], v[38:53]
	ds_read_b64_tr_b16 v[240:241], v5 offset:4608
	ds_read_b64_tr_b16 v[242:243], v5 offset:6656
	v_add_f32_e32 v2, v80, v2
	v_exp_f32_e32 v82, v82
	v_add_f32_e32 v2, v81, v2
	v_exp_f32_e32 v83, v83
	v_add_f32_e32 v2, v82, v2
	v_exp_f32_e32 v84, v84
	s_waitcnt lgkmcnt(6)
	v_mfma_f32_32x32x16_bf16 v[22:37], v[70:73], v[244:247], v[22:37]
	ds_read_b64_tr_b16 v[244:245], v5 offset:5120
	ds_read_b64_tr_b16 v[246:247], v5 offset:7168
	v_add_f32_e32 v2, v83, v2
	v_exp_f32_e32 v85, v85
	v_add_f32_e32 v2, v84, v2
	v_cvt_pk_bf16_f32 v78, v78, v79
	v_add_f32_e32 v2, v85, v2
	s_waitcnt lgkmcnt(6)
	v_mfma_f32_32x32x16_bf16 v[6:21], v[70:73], v[74:77], v[6:21]
	v_cvt_pk_bf16_f32 v79, v80, v81
	v_cvt_pk_bf16_f32 v80, v82, v83
	v_cvt_pk_bf16_f32 v81, v84, v85
	ds_read_b64_tr_b16 v[74:75], v5 offset:5632
	ds_read_b64_tr_b16 v[76:77], v5 offset:7680
	v_permlane32_swap_b32_e32 v78, v80
	v_permlane32_swap_b32_e32 v79, v81
	s_waitcnt lgkmcnt(6)
	s_nop 0
	v_mfma_f32_32x32x16_bf16 v[54:69], v[78:81], v[228:231], v[54:69]
	ds_read_b64_tr_b16 v[228:229], v5 offset:8192
	ds_read_b64_tr_b16 v[230:231], v5 offset:10240
	v_exp_f32_e32 v86, v86
	v_exp_f32_e32 v87, v87
	v_add_f32_e32 v2, v86, v2
	v_exp_f32_e32 v88, v88
	v_add_f32_e32 v2, v87, v2
	v_exp_f32_e32 v89, v89
	s_waitcnt lgkmcnt(6)
	v_mfma_f32_32x32x16_bf16 v[38:53], v[78:81], v[240:243], v[38:53]
	s_min_i32 s3, s100, s101
	s_mul_i32 s98, s3, 0x218000
	s_lshl_b32 s73, s31, 11
	s_add_i32 s73, s73, s53
	s_mov_b32 m0, s73
	v_lshl_add_u64 v[106:107], v[102:103], 0, s[98:99]
	v_lshl_add_u64 v[108:109], v[104:105], 0, s[98:99]
	global_load_lds_dwordx4 v[106:107], off
	ds_read_b64_tr_b16 v[240:241], v5 offset:8704
	ds_read_b64_tr_b16 v[242:243], v5 offset:10752
	v_add_f32_e32 v2, v88, v2
	v_exp_f32_e32 v90, v90
	v_add_f32_e32 v2, v89, v2
	v_exp_f32_e32 v91, v91
	v_add_f32_e32 v2, v90, v2
	v_exp_f32_e32 v92, v92
	s_waitcnt lgkmcnt(6)
	v_mfma_f32_32x32x16_bf16 v[22:37], v[78:81], v[244:247], v[22:37]
	ds_read_b64_tr_b16 v[244:245], v5 offset:9216
	ds_read_b64_tr_b16 v[246:247], v5 offset:11264
	v_add_f32_e32 v2, v91, v2
	v_exp_f32_e32 v93, v93
	v_add_f32_e32 v2, v92, v2
	v_cvt_pk_bf16_f32 v86, v86, v87
	v_add_f32_e32 v2, v93, v2
	s_waitcnt lgkmcnt(6)
	v_mfma_f32_32x32x16_bf16 v[6:21], v[78:81], v[74:77], v[6:21]
	v_cvt_pk_bf16_f32 v87, v88, v89
	v_cvt_pk_bf16_f32 v88, v90, v91
	v_cvt_pk_bf16_f32 v89, v92, v93
	ds_read_b64_tr_b16 v[74:75], v5 offset:9728
	ds_read_b64_tr_b16 v[76:77], v5 offset:11776
	v_permlane32_swap_b32_e32 v86, v88
	v_permlane32_swap_b32_e32 v87, v89
	s_waitcnt lgkmcnt(6)
	s_nop 0
	v_mfma_f32_32x32x16_bf16 v[54:69], v[86:89], v[228:231], v[54:69]
	ds_read_b64_tr_b16 v[228:229], v5 offset:12288
	ds_read_b64_tr_b16 v[230:231], v5 offset:14336
	v_exp_f32_e32 v94, v94
	v_exp_f32_e32 v95, v95
	v_add_f32_e32 v2, v94, v2
	v_exp_f32_e32 v96, v96
	v_add_f32_e32 v2, v95, v2
	v_exp_f32_e32 v97, v97
	s_waitcnt lgkmcnt(6)
	v_mfma_f32_32x32x16_bf16 v[38:53], v[86:89], v[240:243], v[38:53]
	s_add_i32 m0, s73, 0x380
	s_lshl_b32 s3, s31, 10
	s_add_i32 s3, s3, s53
	global_load_lds_dwordx4 v[106:107], off offset:128
	ds_read_b64_tr_b16 v[240:241], v5 offset:12800
	ds_read_b64_tr_b16 v[242:243], v5 offset:14848
	v_add_f32_e32 v2, v96, v2
	v_exp_f32_e32 v98, v98
	v_add_f32_e32 v2, v97, v2
	v_exp_f32_e32 v99, v99
	v_add_f32_e32 v2, v98, v2
	v_exp_f32_e32 v100, v100
	s_waitcnt lgkmcnt(6)
	v_mfma_f32_32x32x16_bf16 v[22:37], v[86:89], v[244:247], v[22:37]
	ds_read_b64_tr_b16 v[244:245], v5 offset:13312
	ds_read_b64_tr_b16 v[246:247], v5 offset:15360
	v_add_f32_e32 v2, v99, v2
	v_exp_f32_e32 v101, v101
	v_add_f32_e32 v2, v100, v2
	v_cvt_pk_bf16_f32 v94, v94, v95
	v_add_f32_e32 v2, v101, v2
	s_waitcnt lgkmcnt(6)
	v_mfma_f32_32x32x16_bf16 v[6:21], v[86:89], v[74:77], v[6:21]
	v_cvt_pk_bf16_f32 v95, v96, v97
	v_cvt_pk_bf16_f32 v96, v98, v99
	v_cvt_pk_bf16_f32 v97, v100, v101
	ds_read_b64_tr_b16 v[74:75], v5 offset:13824
	ds_read_b64_tr_b16 v[76:77], v5 offset:15872
	v_permlane32_swap_b32_e32 v94, v96
	v_permlane32_swap_b32_e32 v95, v97
	v_mov_b32_e32 v3, v2
	s_waitcnt lgkmcnt(6)
	s_nop 0
	v_mfma_f32_32x32x16_bf16 v[54:69], v[94:97], v[228:231], v[54:69]
	v_add_u32_e32 v238, 2, v236
	s_waitcnt lgkmcnt(4)
	v_mfma_f32_32x32x16_bf16 v[38:53], v[94:97], v[240:243], v[38:53]
	s_add_i32 m0, s3, 0x10000
	s_add_i32 s100, s100, 1
	s_add_i32 s53, s53, 0x4000
	global_load_lds_dwordx4 v[108:109], off
	s_and_b32 s53, s53, 0xc000
	v_permlane32_swap_b32_e32 v2, v3
	s_waitcnt lgkmcnt(2)
	v_mfma_f32_32x32x16_bf16 v[22:37], v[94:97], v[244:247], v[22:37]
	s_waitcnt lgkmcnt(0)
	v_mfma_f32_32x32x16_bf16 v[6:21], v[94:97], v[74:77], v[6:21]
	s_and_saveexec_b64 s[10:11], vcc
	s_xor_b64 s[10:11], exec, s[10:11]
	v_add_u32_e32 v236, 2, v236
	s_or_saveexec_b64 s[14:15], s[10:11]
	v_add_f32_e32 v2, v2, v3
	v_add_f32_e32 v219, v219, v2
	s_xor_b64 exec, exec, s[14:15]
	s_cbranch_execz .LBB0_936
	s_and_b32 s29, s60, 0xc000
	s_add_i32 s12, s29, 0x8000
	v_add_u32_e32 v2, s12, v207
	s_waitcnt vmcnt(6)
	s_waitcnt lgkmcnt(0)
	s_barrier
	v_add_u32_e32 v3, v2, v167
	ds_read_b128 v[70:73], v3 offset:32768
	v_add_u32_e32 v3, v2, v212
	ds_read_b128 v[90:93], v3 offset:32768
	v_add_u32_e32 v3, v2, v214
	ds_read_b128 v[94:97], v3 offset:32768
	v_add_u32_e32 v3, v2, v216
	ds_read_b128 v[98:101], v3 offset:32768
	v_add_u32_e32 v3, s12, v211
	ds_read_b128 v[86:89], v3 offset:32768
	v_add_u32_e32 v3, s12, v213
	ds_read_b128 v[228:231], v3 offset:32768
	v_add_u32_e32 v3, s12, v215
	ds_read_b128 v[240:243], v3 offset:32768
	v_add_u32_e32 v3, s12, v217
	ds_read_b128 v[244:247], v3 offset:32768
	v_add_u32_e32 v3, 0x7f, v235
	v_cmp_le_i32_e64 s[10:11], s27, v3
	v_cmp_gt_i32_e32 vcc, s27, v3
	v_cmp_ge_i32_e64 s[12:13], s18, v237
	v_cvt_f32_i32_e32 v2, v237
	s_and_b64 s[10:11], s[10:11], s[12:13]
	s_cmp_eq_u64 s[10:11], 0
	s_cbranch_scc0 .Lattn_nl2
	s_waitcnt lgkmcnt(7)
	v_mfma_f32_32x32x16_bf16 v[70:85], v[70:73], v[114:117], 0
	v_cndmask_b32_e64 v3, -v189, v189, vcc
	v_sub_f32_e32 v2, v191, v2
	v_mul_f32_e64 v2, v2, -v3
	v_cvt_pk_bf16_f32 v5, v2, v3
	v_lshlrev_b32_e32 v196, 16, v5
	v_and_b32_e32 v197, 0xffff0000, v5
	s_waitcnt lgkmcnt(6)
	v_mfma_f32_32x32x16_bf16 v[70:85], v[90:93], v[118:121], v[70:85]
	v_pk_add_f32 v[2:3], v[2:3], v[196:197] neg_lo:[0,1] neg_hi:[0,1]
	s_nop 0
	v_cvt_pk_bf16_f32 v2, v2, v3
	v_and_b32_e32 v3, 0xffff, v5
	v_lshl_or_b32 v183, v2, 16, v3
	s_waitcnt lgkmcnt(5)
	v_mfma_f32_32x32x16_bf16 v[70:85], v[94:97], v[122:125], v[70:85]
	v_lshrrev_b32_e32 v3, 16, v5
	v_and_or_b32 v2, v2, s28, v3
	v_cndmask_b32_e64 v3, 0, v2, s[4:5]
	v_cndmask_b32_e64 v2, 0, v183, s[4:5]
	v_mov_b32_e32 v5, v4
	s_waitcnt lgkmcnt(4)
	v_mfma_f32_32x32x16_bf16 v[70:85], v[98:101], v[126:129], v[70:85]
	s_waitcnt lgkmcnt(3)
	v_mfma_f32_32x32x16_bf16 v[86:101], v[86:89], v[114:117], 0
	s_waitcnt lgkmcnt(2)
	v_mfma_f32_32x32x16_bf16 v[86:101], v[228:231], v[118:121], v[86:101]
	s_waitcnt lgkmcnt(1)
	v_mfma_f32_32x32x16_bf16 v[86:101], v[240:243], v[122:125], v[86:101]
	s_waitcnt lgkmcnt(0)
	v_mfma_f32_32x32x16_bf16 v[86:101], v[244:247], v[126:129], v[86:101]
	v_mfma_f32_32x32x16_bf16 v[70:85], v[110:113], v[2:5], v[70:85]
	v_mfma_f32_32x32x16_bf16 v[86:101], v[176:179], v[2:5], v[86:101]
	s_branch .Lattn_exp2
